# GLU (P4) epilogue: once-read residual loads carry the nt hint
# baseline (speedup 1.0000x reference)
; #define LAS __attribute__((address_space(3)))
; __device__ __forceinline__ float sigmoidf_(float x) { return __builtin_amdgcn_rcpf(1.f + __builtin_amdgcn_exp2f(-1.4426950408889634f * x)); }
; #define EPI_FOR_ROWS for (int ai = 0; ai < 2; ++ai) _Pragma("unroll") for (int m = 0; m < 4; ++m)
; __device__ __forceinline__ u32x4 pack8(const f32x4 a, const f32x4 b) { u32x4 w; w.x = cvt_pk_bf16(a[0], a[1]); w.y = cvt_pk_bf16(a[2], a[3]); w.z = cvt_pk_bf16(b[0], b[1]); w.w = cvt_pk_bf16(b[2], b[3]); return w; }
;     __device__ __forceinline__ void small(size_t row, int col, const f32x4 v0, const f32x4 v1) const { *(u32x4*)(Ub + row * DSSM + col) = pack8(v0, v1); }
;     __device__ __forceinline__ void piece(size_t row, int col, f32x4 v0, f32x4 v1, const f32x4 b0, const f32x4 b1) const {
;     ...
;         if constexpr (MODE == 4) { f32x4 r0, r1; unpack8(*(const u32x4*)(res + row * ldr + col), r0, r1); v0 = v0 + b0; v1 = v1 + b1;
; #pragma unroll
;             for (int e = 0; e < 4; ++e) { v0[e] = r0[e] * sigmoidf_(v0[e]); v1[e] = r1[e] * sigmoidf_(v1[e]); }
;             *(u32x4*)((bf16_t*)O + row * ldo + col) = pack8(v0, v1); }
;     }
;     __device__ __forceinline__ void small(size_t row, int col, const f32x4 v0, const f32x4 v1) const {
;         const f32x4 z = (f32x4){0.f, 0.f, 0.f, 0.f};
;         piece(row, col, v0, v1, (MODE >= 2) ? *(const f32x4*)(bias + col) : z, (MODE >= 2) ? *(const f32x4*)(bias + col + 4) : z);
;     }
;     __device__ __forceinline__ void operator()(const f32x4 (&acc)[2][2][4][2], const Unit& u, int wr, int wc, int fr_, int fq_, LAS unsigned char*) const {
;         int fr = fr_, fq = fq_; asm volatile("" : "+v"(fr), "+v"(fq));
;         const int colb = u.col0 + wc * 32 + 8 * fq;
;         f32x4 bv[2][2];
; #pragma unroll
;         for (int bj = 0; bj < 2; ++bj)
; #pragma unroll
;             for (int n = 0; n < 2; ++n) bv[bj][n] = (MODE >= 2) ? *(const f32x4*)(bias + colb + bj * HALF + 4 * n) : (f32x4){0.f, 0.f, 0.f, 0.f};
; #pragma unroll
;         EPI_FOR_ROWS {
;             const int rl = ai * HALF + wr * 64 + m * 16 + fr; const size_t row = (size_t)u.row0 + rl;
;             if (MODE == 0 && !(u.nvalid >= 0 ? rl < u.nvalid : rl >= 256 + u.nvalid)) continue;
; #pragma unroll
;             for (int bj = 0; bj < 2; ++bj) piece(row, colb + bj * HALF, acc[ai][bj][m][0], acc[ai][bj][m][1], bv[bj][0], bv[bj][1]);
.LBB0_743:
	v_mov_b32_e32 v56, v165
	v_mov_b32_e32 v162, v164
	s_add_i32 s13, s22, s39
	v_readlane_b32 s68, v254, 61
	v_lshl_add_u32 v160, v56, 3, s13
	v_ashrrev_i32_e32 v161, 31, v160
	v_readlane_b32 s72, v255, 1
	v_readlane_b32 s73, v255, 2
	v_add_u32_e32 v162, s38, v162
	s_ashr_i32 s19, s18, 31
	v_lshl_add_u64 v[56:57], v[160:161], 2, s[72:73]
	global_load_dwordx4 v[76:79], v[56:57], off
	global_load_dwordx4 v[72:75], v[56:57], off offset:16
	global_load_dwordx4 v[60:63], v[56:57], off offset:512
	s_nop 0
	global_load_dwordx4 v[56:59], v[56:57], off offset:528
	v_ashrrev_i32_e32 v163, 31, v162
	v_lshl_add_u64 v[174:175], v[162:163], 0, s[18:19]
	v_lshlrev_b64 v[170:171], 10, v[174:175]
	v_lshlrev_b64 v[160:161], 1, v[160:161]
	v_lshl_add_u64 v[170:171], s[46:47], 0, v[170:171]
	v_lshl_add_u64 v[176:177], v[170:171], 0, v[160:161]
	global_load_dwordx4 v[170:173], v[176:177], off nt
	v_lshlrev_b64 v[174:175], 11, v[174:175]
	v_lshl_add_u64 v[174:175], s[8:9], 0, v[174:175]
	v_lshl_add_u64 v[182:183], v[174:175], 0, v[160:161]
	global_load_dwordx4 v[174:177], v[176:177], off offset:256 nt
	v_add_u32_e32 v178, 16, v162
	v_ashrrev_i32_e32 v179, 31, v178
	v_lshl_add_u64 v[178:179], v[178:179], 0, s[18:19]
	v_lshlrev_b64 v[180:181], 10, v[178:179]
	v_lshl_add_u64 v[180:181], s[46:47], 0, v[180:181]
	v_lshl_add_u64 v[180:181], v[180:181], 0, v[160:161]
	s_andn2_b64 vcc, exec, s[4:5]
	s_mov_b64 s[4:5], -1
	v_readlane_b32 s69, v254, 62
	v_readlane_b32 s70, v254, 63
	v_readlane_b32 s71, v255, 0
	v_readlane_b32 s74, v255, 3
	v_readlane_b32 s75, v255, 4
	v_readlane_b32 s76, v255, 5
	v_readlane_b32 s77, v255, 6
	v_readlane_b32 s78, v255, 7
	v_readlane_b32 s79, v255, 8
	v_readlane_b32 s80, v255, 9
	v_readlane_b32 s81, v255, 10
	v_readlane_b32 s82, v255, 11
	v_readlane_b32 s83, v255, 12
	global_load_dwordx4 v[188:191], v[180:181], off nt
	global_load_dwordx4 v[192:195], v[180:181], off offset:256 nt
	v_add_u32_e32 v200, 32, v162
	v_ashrrev_i32_e32 v201, 31, v200
	v_lshl_add_u64 v[252:253], v[200:201], 0, s[18:19]
	v_lshlrev_b64 v[200:201], 10, v[252:253]
	v_lshl_add_u64 v[200:201], s[46:47], 0, v[200:201]
	v_lshl_add_u64 v[200:201], v[200:201], 0, v[160:161]
	global_load_dwordx4 v[196:199], v[200:201], off nt
	global_load_dwordx4 v[204:207], v[200:201], off offset:256 nt
	v_add_u32_e32 v200, 48, v162
	v_ashrrev_i32_e32 v201, 31, v200
	v_lshl_add_u64 v[252:253], v[200:201], 0, s[18:19]
	v_lshlrev_b64 v[200:201], 10, v[252:253]
	v_lshl_add_u64 v[200:201], s[46:47], 0, v[200:201]
	v_lshl_add_u64 v[200:201], v[200:201], 0, v[160:161]
	global_load_dwordx4 v[208:211], v[200:201], off nt
	global_load_dwordx4 v[212:215], v[200:201], off offset:256 nt
	v_add_u32_e32 v200, 0x80, v162
	v_ashrrev_i32_e32 v201, 31, v200
	v_lshl_add_u64 v[252:253], v[200:201], 0, s[18:19]
	v_lshlrev_b64 v[200:201], 10, v[252:253]
	v_lshl_add_u64 v[200:201], s[46:47], 0, v[200:201]
	v_lshl_add_u64 v[200:201], v[200:201], 0, v[160:161]
	global_load_dwordx4 v[216:219], v[200:201], off nt
	global_load_dwordx4 v[220:223], v[200:201], off offset:256 nt
	v_add_u32_e32 v200, 0x90, v162
	v_ashrrev_i32_e32 v201, 31, v200
	v_lshl_add_u64 v[252:253], v[200:201], 0, s[18:19]
	v_lshlrev_b64 v[200:201], 10, v[252:253]
	v_lshl_add_u64 v[200:201], s[46:47], 0, v[200:201]
	v_lshl_add_u64 v[200:201], v[200:201], 0, v[160:161]
	global_load_dwordx4 v[224:227], v[200:201], off nt
	global_load_dwordx4 v[228:231], v[200:201], off offset:256 nt
	v_add_u32_e32 v200, 0xa0, v162
	v_ashrrev_i32_e32 v201, 31, v200
	v_lshl_add_u64 v[252:253], v[200:201], 0, s[18:19]
	v_lshlrev_b64 v[200:201], 10, v[252:253]
	v_lshl_add_u64 v[200:201], s[46:47], 0, v[200:201]
	v_lshl_add_u64 v[200:201], v[200:201], 0, v[160:161]
	global_load_dwordx4 v[232:235], v[200:201], off nt
	global_load_dwordx4 v[236:239], v[200:201], off offset:256 nt
	v_add_u32_e32 v200, 0xb0, v162
	v_ashrrev_i32_e32 v201, 31, v200
	v_lshl_add_u64 v[252:253], v[200:201], 0, s[18:19]
	v_lshlrev_b64 v[200:201], 10, v[252:253]
	v_lshl_add_u64 v[200:201], s[46:47], 0, v[200:201]
	v_lshl_add_u64 v[200:201], v[200:201], 0, v[160:161]
	global_load_dwordx4 v[240:243], v[200:201], off nt
	global_load_dwordx4 v[244:247], v[200:201], off offset:256 nt
	s_waitcnt vmcnt(14)
	v_pk_add_f32 v[142:143], v[142:143], v[78:79]
	v_pk_add_f32 v[140:141], v[140:141], v[76:77]
	v_pk_add_f32 v[136:137], v[136:137], v[72:73]
	v_pk_add_f32 v[138:139], v[138:139], v[74:75]
	v_pk_add_f32 v[184:185], v[134:135], v[62:63]
	v_pk_add_f32 v[186:187], v[132:133], v[60:61]
	v_mul_f32_e32 v132, 0xbfb8aa3b, v140
	v_mul_f32_e32 v133, 0xbfb8aa3b, v136
	v_mul_f32_e32 v134, 0xbfb8aa3b, v141
	v_mul_f32_e32 v135, 0xbfb8aa3b, v137
	v_mul_f32_e32 v136, 0xbfb8aa3b, v142
	v_mul_f32_e32 v137, 0xbfb8aa3b, v138
	v_mul_f32_e32 v138, 0xbfb8aa3b, v143
	v_mul_f32_e32 v139, 0xbfb8aa3b, v139
	v_exp_f32_e32 v132, v132
	v_exp_f32_e32 v133, v133
	v_exp_f32_e32 v134, v134
	v_exp_f32_e32 v135, v135
	v_exp_f32_e32 v136, v136
	v_exp_f32_e32 v137, v137
	v_exp_f32_e32 v138, v138
	v_exp_f32_e32 v139, v139
	v_add_f32_e32 v132, 1.0, v132
	v_add_f32_e32 v133, 1.0, v133
	v_add_f32_e32 v134, 1.0, v134
	v_add_f32_e32 v135, 1.0, v135
	v_add_f32_e32 v136, 1.0, v136
	v_add_f32_e32 v137, 1.0, v137
	v_add_f32_e32 v138, 1.0, v138
	v_add_f32_e32 v139, 1.0, v139
	v_rcp_f32_e32 v132, v132
	v_rcp_f32_e32 v133, v133
	v_rcp_f32_e32 v134, v134
	v_rcp_f32_e32 v135, v135
	v_rcp_f32_e32 v136, v136
	v_rcp_f32_e32 v137, v137
	v_rcp_f32_e32 v138, v138
	v_rcp_f32_e32 v139, v139
	v_lshlrev_b32_e32 v140, 16, v170
	v_and_b32_e32 v141, 0xffff0000, v170
	v_lshlrev_b32_e32 v142, 16, v171
	v_lshlrev_b32_e32 v163, 16, v172
	v_and_b32_e32 v170, 0xffff0000, v172
; __device__ __forceinline__ float sigmoidf_(float x) { return __builtin_amdgcn_rcpf(1.f + __builtin_amdgcn_exp2f(-1.4426950408889634f * x)); }
; __device__ __forceinline__ u32x4 pack8(const f32x4 a, const f32x4 b) { u32x4 w; w.x = cvt_pk_bf16(a[0], a[1]); w.y = cvt_pk_bf16(a[2], a[3]); w.z = cvt_pk_bf16(b[0], b[1]); w.w = cvt_pk_bf16(b[2], b[3]); return w; }
; __device__ __forceinline__ void unpack8(const u32x4 w, f32x4& a, f32x4& b) { a = (f32x4){bf_lo(w.x), bf_hi(w.x), bf_lo(w.y), bf_hi(w.y)}; b = (f32x4){bf_lo(w.z), bf_hi(w.z), bf_lo(w.w), bf_hi(w.w)}; }
;     __device__ __forceinline__ void piece(size_t row, int col, f32x4 v0, f32x4 v1, const f32x4 b0, const f32x4 b1) const {
;     ...
;         if constexpr (MODE == 4) { f32x4 r0, r1; unpack8(*(const u32x4*)(res + row * ldr + col), r0, r1); v0 = v0 + b0; v1 = v1 + b1;
; #pragma unroll
;             for (int e = 0; e < 4; ++e) { v0[e] = r0[e] * sigmoidf_(v0[e]); v1[e] = r1[e] * sigmoidf_(v1[e]); }
;             *(u32x4*)((bf16_t*)O + row * ldo + col) = pack8(v0, v1); }
	v_and_b32_e32 v143, 0xffff0000, v171
	v_lshlrev_b32_e32 v171, 16, v173
	v_and_b32_e32 v172, 0xffff0000, v173
	v_mul_f32_e32 v132, v132, v140
	v_mul_f32_e32 v140, v133, v163
	v_mul_f32_e32 v133, v134, v141
	v_mul_f32_e32 v134, v135, v170
	v_mul_f32_e32 v135, v136, v142
	v_mul_f32_e32 v136, v137, v171
	v_mul_f32_e32 v137, v138, v143
	v_mul_f32_e32 v138, v139, v172
	v_cvt_pk_bf16_f32 v132, v132, v133
	v_cvt_pk_bf16_f32 v133, v135, v137
	v_cvt_pk_bf16_f32 v134, v140, v134
	v_cvt_pk_bf16_f32 v135, v136, v138
	global_store_dwordx4 v[182:183], v[132:135], off
	v_pk_add_f32 v[122:123], v[122:123], v[58:59]
	v_pk_add_f32 v[120:121], v[120:121], v[56:57]
	v_mul_f32_e32 v136, 0xbfb8aa3b, v186
	v_mul_f32_e32 v120, 0xbfb8aa3b, v120
	v_mul_f32_e32 v137, 0xbfb8aa3b, v187
	v_mul_f32_e32 v121, 0xbfb8aa3b, v121
	v_mul_f32_e32 v138, 0xbfb8aa3b, v184
	v_mul_f32_e32 v122, 0xbfb8aa3b, v122
	v_mul_f32_e32 v139, 0xbfb8aa3b, v185
	v_mul_f32_e32 v123, 0xbfb8aa3b, v123
	v_exp_f32_e32 v136, v136
	v_exp_f32_e32 v120, v120
	v_exp_f32_e32 v137, v137
	v_exp_f32_e32 v121, v121
	v_exp_f32_e32 v138, v138
	v_exp_f32_e32 v122, v122
	v_exp_f32_e32 v139, v139
	v_exp_f32_e32 v123, v123
	v_add_f32_e32 v136, 1.0, v136
	v_add_f32_e32 v120, 1.0, v120
	v_add_f32_e32 v137, 1.0, v137
	v_add_f32_e32 v121, 1.0, v121
	v_add_f32_e32 v138, 1.0, v138
	v_add_f32_e32 v122, 1.0, v122
	v_add_f32_e32 v139, 1.0, v139
	v_add_f32_e32 v123, 1.0, v123
	v_rcp_f32_e32 v136, v136
	v_rcp_f32_e32 v120, v120
	v_rcp_f32_e32 v137, v137
	v_rcp_f32_e32 v121, v121
	v_rcp_f32_e32 v138, v138
	v_rcp_f32_e32 v122, v122
	v_rcp_f32_e32 v139, v139
	v_rcp_f32_e32 v123, v123
	v_lshlrev_b32_e32 v140, 16, v174
	v_and_b32_e32 v141, 0xffff0000, v174
	v_lshlrev_b32_e32 v142, 16, v175
	v_and_b32_e32 v143, 0xffff0000, v175
	v_lshlrev_b32_e32 v163, 16, v176
	v_and_b32_e32 v170, 0xffff0000, v176
	v_lshlrev_b32_e32 v171, 16, v177
	v_and_b32_e32 v172, 0xffff0000, v177
	v_mul_f32_e32 v136, v136, v140
	v_mul_f32_e32 v140, v120, v163
	v_mul_f32_e32 v120, v137, v141
	v_mul_f32_e32 v137, v121, v170
	v_mul_f32_e32 v121, v138, v142
	v_mul_f32_e32 v138, v122, v171
	v_mul_f32_e32 v122, v139, v143
	v_mul_f32_e32 v123, v123, v172
	v_cvt_pk_bf16_f32 v120, v136, v120
	v_cvt_pk_bf16_f32 v121, v121, v122
	v_cvt_pk_bf16_f32 v122, v140, v137
	v_cvt_pk_bf16_f32 v123, v138, v123
	global_store_dwordx4 v[182:183], v[120:123], off offset:256
	v_pk_add_f32 v[128:129], v[128:129], v[76:77]
	v_pk_add_f32 v[124:125], v[124:125], v[72:73]
	v_mul_f32_e32 v128, 0xbfb8aa3b, v128
	v_mul_f32_e32 v124, 0xbfb8aa3b, v124
	v_mul_f32_e32 v129, 0xbfb8aa3b, v129
	v_mul_f32_e32 v125, 0xbfb8aa3b, v125
	v_exp_f32_e32 v128, v128
	v_exp_f32_e32 v124, v124
	v_exp_f32_e32 v129, v129
	v_exp_f32_e32 v125, v125
	v_pk_add_f32 v[130:131], v[130:131], v[78:79]
	v_add_f32_e32 v128, 1.0, v128
	v_mul_f32_e32 v130, 0xbfb8aa3b, v130
	v_add_f32_e32 v124, 1.0, v124
	v_add_f32_e32 v129, 1.0, v129
	v_add_f32_e32 v125, 1.0, v125
	v_exp_f32_e32 v130, v130
	v_rcp_f32_e32 v128, v128
	v_rcp_f32_e32 v124, v124
	v_rcp_f32_e32 v129, v129
	v_rcp_f32_e32 v125, v125
	v_pk_add_f32 v[126:127], v[126:127], v[74:75]
	v_pk_add_f32 v[116:117], v[116:117], v[60:61]
	s_waitcnt vmcnt(15)
	v_lshlrev_b32_e32 v136, 16, v188
	v_and_b32_e32 v132, 0xffff0000, v188
	v_lshlrev_b32_e32 v138, 16, v190
	v_and_b32_e32 v134, 0xffff0000, v190
	v_mul_f32_e32 v126, 0xbfb8aa3b, v126
	v_mul_f32_e32 v128, v128, v136
	v_mul_f32_e32 v136, v124, v138
	v_mul_f32_e32 v124, v129, v132
	v_mul_f32_e32 v129, v125, v134
	v_add_f32_e32 v125, 1.0, v130
	v_mul_f32_e32 v130, 0xbfb8aa3b, v131
	v_exp_f32_e32 v126, v126
	v_exp_f32_e32 v130, v130
	v_mul_f32_e32 v127, 0xbfb8aa3b, v127
	v_exp_f32_e32 v127, v127
	v_add_f32_e32 v126, 1.0, v126
	v_add_f32_e32 v130, 1.0, v130
	v_rcp_f32_e32 v125, v125
	v_rcp_f32_e32 v126, v126
	v_rcp_f32_e32 v130, v130
	v_add_f32_e32 v127, 1.0, v127
	v_lshlrev_b32_e32 v137, 16, v189
	v_and_b32_e32 v133, 0xffff0000, v189
	v_lshlrev_b32_e32 v139, 16, v191
	v_rcp_f32_e32 v127, v127
	v_mul_f32_e32 v125, v125, v137
	v_mul_f32_e32 v131, v126, v139
	v_mul_f32_e32 v126, v130, v133
	v_cvt_pk_bf16_f32 v124, v128, v124
	v_cvt_pk_bf16_f32 v125, v125, v126
	v_cvt_pk_bf16_f32 v126, v136, v129
	v_lshlrev_b64 v[128:129], 11, v[178:179]
	v_and_b32_e32 v135, 0xffff0000, v191
	v_lshl_add_u64 v[128:129], s[8:9], 0, v[128:129]
	v_mul_f32_e32 v127, v127, v135
	v_lshl_add_u64 v[128:129], v[128:129], 0, v[160:161]
	v_cvt_pk_bf16_f32 v127, v131, v127
	global_store_dwordx4 v[128:129], v[124:127], off
	v_pk_add_f32 v[112:113], v[112:113], v[56:57]
	v_mul_f32_e32 v116, 0xbfb8aa3b, v116
	v_add_u32_e32 v124, 32, v162
	v_ashrrev_i32_e32 v125, 31, v124
	v_lshl_add_u64 v[130:131], v[124:125], 0, s[18:19]
	v_lshlrev_b64 v[124:125], 10, v[130:131]
	v_lshl_add_u64 v[124:125], s[46:47], 0, v[124:125]
	v_lshl_add_u64 v[132:133], v[124:125], 0, v[160:161]
	v_mul_f32_e32 v112, 0xbfb8aa3b, v112
	v_mul_f32_e32 v117, 0xbfb8aa3b, v117
	v_exp_f32_e32 v116, v116
	v_exp_f32_e32 v112, v112
	v_exp_f32_e32 v117, v117
	v_mul_f32_e32 v113, 0xbfb8aa3b, v113
	v_add_f32_e32 v116, 1.0, v116
	v_add_f32_e32 v112, 1.0, v112
	v_add_f32_e32 v117, 1.0, v117
	v_rcp_f32_e32 v116, v116
	v_rcp_f32_e32 v112, v112
	v_rcp_f32_e32 v117, v117
	v_exp_f32_e32 v113, v113
	s_waitcnt vmcnt(15)
; __device__ __forceinline__ float sigmoidf_(float x) { return __builtin_amdgcn_rcpf(1.f + __builtin_amdgcn_exp2f(-1.4426950408889634f * x)); }
; __device__ __forceinline__ u32x4 pack8(const f32x4 a, const f32x4 b) { u32x4 w; w.x = cvt_pk_bf16(a[0], a[1]); w.y = cvt_pk_bf16(a[2], a[3]); w.z = cvt_pk_bf16(b[0], b[1]); w.w = cvt_pk_bf16(b[2], b[3]); return w; }
; __device__ __forceinline__ void unpack8(const u32x4 w, f32x4& a, f32x4& b) { a = (f32x4){bf_lo(w.x), bf_hi(w.x), bf_lo(w.y), bf_hi(w.y)}; b = (f32x4){bf_lo(w.z), bf_hi(w.z), bf_lo(w.w), bf_hi(w.w)}; }
;     __device__ __forceinline__ void piece(size_t row, int col, f32x4 v0, f32x4 v1, const f32x4 b0, const f32x4 b1) const {
;     ...
;         if constexpr (MODE == 4) { f32x4 r0, r1; unpack8(*(const u32x4*)(res + row * ldr + col), r0, r1); v0 = v0 + b0; v1 = v1 + b1;
; #pragma unroll
;             for (int e = 0; e < 4; ++e) { v0[e] = r0[e] * sigmoidf_(v0[e]); v1[e] = r1[e] * sigmoidf_(v1[e]); }
;             *(u32x4*)((bf16_t*)O + row * ldo + col) = pack8(v0, v1); }
	v_lshlrev_b32_e32 v134, 16, v192
	v_and_b32_e32 v120, 0xffff0000, v192
	v_lshlrev_b32_e32 v136, 16, v194
	v_pk_add_f32 v[118:119], v[118:119], v[62:63]
	v_mul_f32_e32 v116, v116, v134
	v_mul_f32_e32 v134, v112, v136
	v_mul_f32_e32 v112, v117, v120
	v_add_f32_e32 v113, 1.0, v113
	v_mul_f32_e32 v117, 0xbfb8aa3b, v118
	v_rcp_f32_e32 v113, v113
	v_exp_f32_e32 v117, v117
	v_and_b32_e32 v122, 0xffff0000, v194
	v_pk_add_f32 v[114:115], v[114:115], v[58:59]
	v_mul_f32_e32 v118, v113, v122
	v_mul_f32_e32 v114, 0xbfb8aa3b, v114
	v_add_f32_e32 v113, 1.0, v117
	v_mul_f32_e32 v117, 0xbfb8aa3b, v119
	v_mul_f32_e32 v115, 0xbfb8aa3b, v115
	v_exp_f32_e32 v114, v114
	v_exp_f32_e32 v117, v117
	v_exp_f32_e32 v115, v115
	v_rcp_f32_e32 v113, v113
	v_add_f32_e32 v114, 1.0, v114
	v_add_f32_e32 v117, 1.0, v117
	v_add_f32_e32 v115, 1.0, v115
	v_rcp_f32_e32 v114, v114
	v_rcp_f32_e32 v117, v117
	v_rcp_f32_e32 v115, v115
	v_lshlrev_b32_e32 v135, 16, v193
	v_and_b32_e32 v121, 0xffff0000, v193
	v_lshlrev_b32_e32 v137, 16, v195
	v_and_b32_e32 v123, 0xffff0000, v195
	v_mul_f32_e32 v113, v113, v135
	v_mul_f32_e32 v119, v114, v137
	v_mul_f32_e32 v114, v117, v121
	v_mul_f32_e32 v115, v115, v123
	v_cvt_pk_bf16_f32 v112, v116, v112
	v_cvt_pk_bf16_f32 v113, v113, v114
	v_cvt_pk_bf16_f32 v114, v134, v118
	v_cvt_pk_bf16_f32 v115, v119, v115
	global_store_dwordx4 v[128:129], v[112:115], off offset:256
	v_pk_add_f32 v[108:109], v[108:109], v[76:77]
	v_pk_add_f32 v[104:105], v[104:105], v[72:73]
	v_mul_f32_e32 v108, 0xbfb8aa3b, v108
	v_mul_f32_e32 v104, 0xbfb8aa3b, v104
	v_mul_f32_e32 v109, 0xbfb8aa3b, v109
	v_exp_f32_e32 v108, v108
	v_exp_f32_e32 v104, v104
	v_exp_f32_e32 v109, v109
	v_mul_f32_e32 v105, 0xbfb8aa3b, v105
	v_add_f32_e32 v108, 1.0, v108
	v_add_f32_e32 v104, 1.0, v104
	v_add_f32_e32 v109, 1.0, v109
	v_rcp_f32_e32 v108, v108
	v_rcp_f32_e32 v104, v104
	v_rcp_f32_e32 v109, v109
	v_exp_f32_e32 v105, v105
	v_pk_add_f32 v[110:111], v[110:111], v[78:79]
	v_pk_add_f32 v[106:107], v[106:107], v[74:75]
	v_pk_add_f32 v[100:101], v[100:101], v[60:61]
	v_add_f32_e32 v105, 1.0, v105
	v_rcp_f32_e32 v105, v105
	v_mul_f32_e32 v106, 0xbfb8aa3b, v106
	v_exp_f32_e32 v106, v106
	v_mul_f32_e32 v107, 0xbfb8aa3b, v107
	s_waitcnt vmcnt(15)
	v_lshlrev_b32_e32 v116, 16, v196
	v_and_b32_e32 v117, 0xffff0000, v196
	v_lshlrev_b32_e32 v120, 16, v198
	v_mul_f32_e32 v108, v108, v116
	v_mul_f32_e32 v116, v104, v120
	v_mul_f32_e32 v104, v109, v117
	v_mul_f32_e32 v109, 0xbfb8aa3b, v110
	v_exp_f32_e32 v109, v109
	v_and_b32_e32 v121, 0xffff0000, v198
	v_mul_f32_e32 v110, v105, v121
	v_exp_f32_e32 v107, v107
	v_add_f32_e32 v105, 1.0, v109
	v_mul_f32_e32 v109, 0xbfb8aa3b, v111
	v_exp_f32_e32 v109, v109
	v_add_f32_e32 v106, 1.0, v106
	v_rcp_f32_e32 v106, v106
	v_add_f32_e32 v107, 1.0, v107
	v_add_f32_e32 v109, 1.0, v109
	v_rcp_f32_e32 v109, v109
	v_rcp_f32_e32 v105, v105
	v_rcp_f32_e32 v107, v107
	v_and_b32_e32 v119, 0xffff0000, v197
	v_lshlrev_b32_e32 v122, 16, v199
	v_mul_f32_e32 v111, v106, v122
	v_mul_f32_e32 v106, v109, v119
	v_cvt_pk_bf16_f32 v104, v108, v104
	v_lshlrev_b64 v[108:109], 11, v[130:131]
	v_lshlrev_b32_e32 v118, 16, v197
	v_and_b32_e32 v123, 0xffff0000, v199
	v_lshl_add_u64 v[108:109], s[8:9], 0, v[108:109]
	v_mul_f32_e32 v105, v105, v118
	v_mul_f32_e32 v107, v107, v123
	v_lshl_add_u64 v[108:109], v[108:109], 0, v[160:161]
	v_cvt_pk_bf16_f32 v105, v105, v106
	v_cvt_pk_bf16_f32 v106, v116, v110
	v_cvt_pk_bf16_f32 v107, v111, v107
	global_store_dwordx4 v[108:109], v[104:107], off
	v_pk_add_f32 v[96:97], v[96:97], v[56:57]
	v_mul_f32_e32 v100, 0xbfb8aa3b, v100
	v_add_u32_e32 v104, 48, v162
	v_ashrrev_i32_e32 v105, 31, v104
	v_lshl_add_u64 v[110:111], v[104:105], 0, s[18:19]
	v_lshlrev_b64 v[104:105], 10, v[110:111]
	v_lshl_add_u64 v[104:105], s[46:47], 0, v[104:105]
	v_lshl_add_u64 v[116:117], v[104:105], 0, v[160:161]
	v_mul_f32_e32 v96, 0xbfb8aa3b, v96
	v_mul_f32_e32 v101, 0xbfb8aa3b, v101
	v_exp_f32_e32 v100, v100
	v_exp_f32_e32 v96, v96
	v_exp_f32_e32 v101, v101
	v_mul_f32_e32 v97, 0xbfb8aa3b, v97
	v_add_f32_e32 v100, 1.0, v100
	v_add_f32_e32 v96, 1.0, v96
	v_add_f32_e32 v101, 1.0, v101
	v_rcp_f32_e32 v100, v100
	v_rcp_f32_e32 v96, v96
	v_rcp_f32_e32 v101, v101
	v_exp_f32_e32 v97, v97
	s_waitcnt vmcnt(15)
	v_lshlrev_b32_e32 v118, 16, v204
	v_and_b32_e32 v112, 0xffff0000, v204
	v_lshlrev_b32_e32 v120, 16, v206
	v_pk_add_f32 v[102:103], v[102:103], v[62:63]
	v_mul_f32_e32 v100, v100, v118
	v_mul_f32_e32 v118, v96, v120
	v_mul_f32_e32 v96, v101, v112
	v_add_f32_e32 v97, 1.0, v97
	v_mul_f32_e32 v101, 0xbfb8aa3b, v102
	v_rcp_f32_e32 v97, v97
	v_exp_f32_e32 v101, v101
	v_and_b32_e32 v114, 0xffff0000, v206
	v_pk_add_f32 v[98:99], v[98:99], v[58:59]
	v_mul_f32_e32 v102, v97, v114
	v_mul_f32_e32 v98, 0xbfb8aa3b, v98
	v_add_f32_e32 v97, 1.0, v101
	v_mul_f32_e32 v101, 0xbfb8aa3b, v103
	v_mul_f32_e32 v99, 0xbfb8aa3b, v99
	v_exp_f32_e32 v98, v98
	v_exp_f32_e32 v101, v101
	v_exp_f32_e32 v99, v99
	v_rcp_f32_e32 v97, v97
	v_add_f32_e32 v98, 1.0, v98
	v_add_f32_e32 v101, 1.0, v101
	v_add_f32_e32 v99, 1.0, v99
	v_rcp_f32_e32 v98, v98
	v_rcp_f32_e32 v101, v101
	v_rcp_f32_e32 v99, v99
	v_lshlrev_b32_e32 v119, 16, v205
	v_and_b32_e32 v113, 0xffff0000, v205
	v_lshlrev_b32_e32 v121, 16, v207
	v_and_b32_e32 v115, 0xffff0000, v207
	v_mul_f32_e32 v97, v97, v119
	v_mul_f32_e32 v103, v98, v121
	v_mul_f32_e32 v98, v101, v113
	v_mul_f32_e32 v99, v99, v115
	v_cvt_pk_bf16_f32 v96, v100, v96
	v_cvt_pk_bf16_f32 v97, v97, v98
	v_cvt_pk_bf16_f32 v98, v118, v102
	v_cvt_pk_bf16_f32 v99, v103, v99
	global_store_dwordx4 v[108:109], v[96:99], off offset:256
	v_pk_add_f32 v[92:93], v[92:93], v[76:77]
	v_pk_add_f32 v[88:89], v[88:89], v[72:73]
	v_mul_f32_e32 v92, 0xbfb8aa3b, v92
	v_mul_f32_e32 v88, 0xbfb8aa3b, v88
	v_mul_f32_e32 v93, 0xbfb8aa3b, v93
	v_exp_f32_e32 v92, v92
	v_exp_f32_e32 v88, v88
	v_exp_f32_e32 v93, v93
	v_mul_f32_e32 v89, 0xbfb8aa3b, v89
	v_add_f32_e32 v92, 1.0, v92
	v_add_f32_e32 v88, 1.0, v88
	v_add_f32_e32 v93, 1.0, v93
	v_rcp_f32_e32 v92, v92
	v_rcp_f32_e32 v88, v88
	v_rcp_f32_e32 v93, v93
	v_exp_f32_e32 v89, v89
	v_pk_add_f32 v[94:95], v[94:95], v[78:79]
	v_pk_add_f32 v[90:91], v[90:91], v[74:75]
	v_pk_add_f32 v[84:85], v[84:85], v[60:61]
	v_add_f32_e32 v89, 1.0, v89
	v_rcp_f32_e32 v89, v89
	v_mul_f32_e32 v90, 0xbfb8aa3b, v90
	v_exp_f32_e32 v90, v90
	v_mul_f32_e32 v91, 0xbfb8aa3b, v91
	s_waitcnt vmcnt(15)
; __device__ __forceinline__ float sigmoidf_(float x) { return __builtin_amdgcn_rcpf(1.f + __builtin_amdgcn_exp2f(-1.4426950408889634f * x)); }
; __device__ __forceinline__ u32x4 pack8(const f32x4 a, const f32x4 b) { u32x4 w; w.x = cvt_pk_bf16(a[0], a[1]); w.y = cvt_pk_bf16(a[2], a[3]); w.z = cvt_pk_bf16(b[0], b[1]); w.w = cvt_pk_bf16(b[2], b[3]); return w; }
; __device__ __forceinline__ void unpack8(const u32x4 w, f32x4& a, f32x4& b) { a = (f32x4){bf_lo(w.x), bf_hi(w.x), bf_lo(w.y), bf_hi(w.y)}; b = (f32x4){bf_lo(w.z), bf_hi(w.z), bf_lo(w.w), bf_hi(w.w)}; }
;     __device__ __forceinline__ void piece(size_t row, int col, f32x4 v0, f32x4 v1, const f32x4 b0, const f32x4 b1) const {
;     ...
;         if constexpr (MODE == 4) { f32x4 r0, r1; unpack8(*(const u32x4*)(res + row * ldr + col), r0, r1); v0 = v0 + b0; v1 = v1 + b1;
; #pragma unroll
;             for (int e = 0; e < 4; ++e) { v0[e] = r0[e] * sigmoidf_(v0[e]); v1[e] = r1[e] * sigmoidf_(v1[e]); }
;             *(u32x4*)((bf16_t*)O + row * ldo + col) = pack8(v0, v1); }
	v_lshlrev_b32_e32 v100, 16, v208
	v_and_b32_e32 v101, 0xffff0000, v208
	v_lshlrev_b32_e32 v104, 16, v210
	v_mul_f32_e32 v92, v92, v100
	v_mul_f32_e32 v100, v88, v104
	v_mul_f32_e32 v88, v93, v101
	v_mul_f32_e32 v93, 0xbfb8aa3b, v94
	v_exp_f32_e32 v93, v93
	v_lshlrev_b32_e32 v102, 16, v209
	v_and_b32_e32 v103, 0xffff0000, v209
	v_and_b32_e32 v105, 0xffff0000, v210
	v_mul_f32_e32 v94, v89, v105
	v_add_f32_e32 v89, 1.0, v93
	v_mul_f32_e32 v93, 0xbfb8aa3b, v95
	v_exp_f32_e32 v93, v93
	v_exp_f32_e32 v91, v91
	v_add_f32_e32 v90, 1.0, v90
	v_rcp_f32_e32 v90, v90
	v_add_f32_e32 v93, 1.0, v93
	v_rcp_f32_e32 v93, v93
	v_add_f32_e32 v91, 1.0, v91
	v_rcp_f32_e32 v89, v89
	v_rcp_f32_e32 v91, v91
	v_lshlrev_b32_e32 v106, 16, v211
	v_mul_f32_e32 v95, v90, v106
	v_mul_f32_e32 v90, v93, v103
	v_cvt_pk_bf16_f32 v88, v92, v88
	v_lshlrev_b64 v[92:93], 11, v[110:111]
	v_and_b32_e32 v107, 0xffff0000, v211
	v_lshl_add_u64 v[92:93], s[8:9], 0, v[92:93]
	v_mul_f32_e32 v89, v89, v102
	v_mul_f32_e32 v91, v91, v107
	v_lshl_add_u64 v[92:93], v[92:93], 0, v[160:161]
	v_cvt_pk_bf16_f32 v89, v89, v90
	v_cvt_pk_bf16_f32 v90, v100, v94
	v_cvt_pk_bf16_f32 v91, v95, v91
	global_store_dwordx4 v[92:93], v[88:91], off
	v_pk_add_f32 v[80:81], v[80:81], v[56:57]
	v_mul_f32_e32 v84, 0xbfb8aa3b, v84
	v_add_u32_e32 v88, 0x80, v162
	v_ashrrev_i32_e32 v89, 31, v88
	v_lshl_add_u64 v[94:95], v[88:89], 0, s[18:19]
	v_lshlrev_b64 v[88:89], 10, v[94:95]
	v_lshl_add_u64 v[88:89], s[46:47], 0, v[88:89]
	v_lshl_add_u64 v[100:101], v[88:89], 0, v[160:161]
	v_mul_f32_e32 v80, 0xbfb8aa3b, v80
	v_mul_f32_e32 v85, 0xbfb8aa3b, v85
	v_exp_f32_e32 v84, v84
	v_exp_f32_e32 v80, v80
	v_exp_f32_e32 v85, v85
	v_mul_f32_e32 v81, 0xbfb8aa3b, v81
	v_add_f32_e32 v84, 1.0, v84
	v_add_f32_e32 v80, 1.0, v80
	v_add_f32_e32 v85, 1.0, v85
	v_rcp_f32_e32 v84, v84
	v_rcp_f32_e32 v80, v80
	v_rcp_f32_e32 v85, v85
	v_exp_f32_e32 v81, v81
	s_waitcnt vmcnt(15)
	v_lshlrev_b32_e32 v102, 16, v212
	v_and_b32_e32 v96, 0xffff0000, v212
	v_lshlrev_b32_e32 v104, 16, v214
	v_pk_add_f32 v[86:87], v[86:87], v[62:63]
	v_mul_f32_e32 v84, v84, v102
	v_mul_f32_e32 v102, v80, v104
	v_mul_f32_e32 v80, v85, v96
	v_add_f32_e32 v81, 1.0, v81
	v_mul_f32_e32 v85, 0xbfb8aa3b, v86
	v_rcp_f32_e32 v81, v81
	v_exp_f32_e32 v85, v85
	v_and_b32_e32 v98, 0xffff0000, v214
	v_pk_add_f32 v[82:83], v[82:83], v[58:59]
	v_mul_f32_e32 v86, v81, v98
	v_mul_f32_e32 v82, 0xbfb8aa3b, v82
	v_add_f32_e32 v81, 1.0, v85
	v_mul_f32_e32 v85, 0xbfb8aa3b, v87
	v_mul_f32_e32 v83, 0xbfb8aa3b, v83
	v_exp_f32_e32 v82, v82
	v_exp_f32_e32 v85, v85
	v_exp_f32_e32 v83, v83
	v_rcp_f32_e32 v81, v81
	v_add_f32_e32 v82, 1.0, v82
	v_add_f32_e32 v85, 1.0, v85
	v_add_f32_e32 v83, 1.0, v83
	v_rcp_f32_e32 v82, v82
	v_rcp_f32_e32 v85, v85
	v_rcp_f32_e32 v83, v83
	v_lshlrev_b32_e32 v103, 16, v213
	v_and_b32_e32 v97, 0xffff0000, v213
	v_lshlrev_b32_e32 v105, 16, v215
	v_and_b32_e32 v99, 0xffff0000, v215
	v_mul_f32_e32 v81, v81, v103
	v_mul_f32_e32 v87, v82, v105
	v_mul_f32_e32 v82, v85, v97
	v_mul_f32_e32 v83, v83, v99
	v_cvt_pk_bf16_f32 v80, v84, v80
	v_cvt_pk_bf16_f32 v81, v81, v82
	v_cvt_pk_bf16_f32 v82, v102, v86
	v_cvt_pk_bf16_f32 v83, v87, v83
	global_store_dwordx4 v[92:93], v[80:83], off offset:256
	v_pk_add_f32 v[68:69], v[68:69], v[76:77]
	v_pk_add_f32 v[64:65], v[64:65], v[72:73]
	v_mul_f32_e32 v68, 0xbfb8aa3b, v68
	v_mul_f32_e32 v64, 0xbfb8aa3b, v64
	v_mul_f32_e32 v69, 0xbfb8aa3b, v69
	v_exp_f32_e32 v68, v68
	v_exp_f32_e32 v64, v64
	v_exp_f32_e32 v69, v69
	v_mul_f32_e32 v65, 0xbfb8aa3b, v65
	v_add_f32_e32 v68, 1.0, v68
	v_add_f32_e32 v64, 1.0, v64
	v_add_f32_e32 v69, 1.0, v69
	v_rcp_f32_e32 v68, v68
	v_rcp_f32_e32 v64, v64
	v_rcp_f32_e32 v69, v69
	v_exp_f32_e32 v65, v65
	v_pk_add_f32 v[70:71], v[70:71], v[78:79]
	v_pk_add_f32 v[66:67], v[66:67], v[74:75]
	v_pk_add_f32 v[52:53], v[52:53], v[60:61]
	v_add_f32_e32 v65, 1.0, v65
	v_rcp_f32_e32 v65, v65
	v_mul_f32_e32 v66, 0xbfb8aa3b, v66
	v_exp_f32_e32 v66, v66
	v_mul_f32_e32 v67, 0xbfb8aa3b, v67
	s_waitcnt vmcnt(15)
	v_lshlrev_b32_e32 v84, 16, v216
	v_and_b32_e32 v85, 0xffff0000, v216
	v_lshlrev_b32_e32 v88, 16, v218
	v_mul_f32_e32 v68, v68, v84
	v_mul_f32_e32 v84, v64, v88
	v_mul_f32_e32 v64, v69, v85
	v_mul_f32_e32 v69, 0xbfb8aa3b, v70
	v_exp_f32_e32 v69, v69
	v_lshlrev_b32_e32 v86, 16, v217
	v_and_b32_e32 v87, 0xffff0000, v217
	v_and_b32_e32 v89, 0xffff0000, v218
	v_mul_f32_e32 v70, v65, v89
	v_add_f32_e32 v65, 1.0, v69
	v_mul_f32_e32 v69, 0xbfb8aa3b, v71
	v_exp_f32_e32 v69, v69
	v_exp_f32_e32 v67, v67
	v_add_f32_e32 v66, 1.0, v66
	v_rcp_f32_e32 v66, v66
	v_add_f32_e32 v69, 1.0, v69
	v_rcp_f32_e32 v69, v69
	v_add_f32_e32 v67, 1.0, v67
	v_rcp_f32_e32 v65, v65
	v_rcp_f32_e32 v67, v67
	v_lshlrev_b32_e32 v90, 16, v219
	v_mul_f32_e32 v71, v66, v90
	v_mul_f32_e32 v66, v69, v87
	v_cvt_pk_bf16_f32 v64, v68, v64
	v_lshlrev_b64 v[68:69], 11, v[94:95]
	v_and_b32_e32 v91, 0xffff0000, v219
	v_lshl_add_u64 v[68:69], s[8:9], 0, v[68:69]
	v_mul_f32_e32 v65, v65, v86
	v_mul_f32_e32 v67, v67, v91
	v_lshl_add_u64 v[68:69], v[68:69], 0, v[160:161]
	v_cvt_pk_bf16_f32 v65, v65, v66
	v_cvt_pk_bf16_f32 v66, v84, v70
	v_cvt_pk_bf16_f32 v67, v71, v67
	global_store_dwordx4 v[68:69], v[64:67], off
	v_pk_add_f32 v[48:49], v[48:49], v[56:57]
	v_mul_f32_e32 v52, 0xbfb8aa3b, v52
	v_add_u32_e32 v64, 0x90, v162
	v_ashrrev_i32_e32 v65, 31, v64
	v_lshl_add_u64 v[70:71], v[64:65], 0, s[18:19]
	v_lshlrev_b64 v[64:65], 10, v[70:71]
	v_lshl_add_u64 v[64:65], s[46:47], 0, v[64:65]
	v_lshl_add_u64 v[84:85], v[64:65], 0, v[160:161]
	v_mul_f32_e32 v48, 0xbfb8aa3b, v48
	v_mul_f32_e32 v53, 0xbfb8aa3b, v53
	v_exp_f32_e32 v52, v52
	v_exp_f32_e32 v48, v48
	v_exp_f32_e32 v53, v53
	v_mul_f32_e32 v49, 0xbfb8aa3b, v49
	v_add_f32_e32 v52, 1.0, v52
	v_add_f32_e32 v48, 1.0, v48
	v_add_f32_e32 v53, 1.0, v53
	v_rcp_f32_e32 v52, v52
	v_rcp_f32_e32 v48, v48
	v_rcp_f32_e32 v53, v53
	v_exp_f32_e32 v49, v49
	s_waitcnt vmcnt(15)
; __device__ __forceinline__ float sigmoidf_(float x) { return __builtin_amdgcn_rcpf(1.f + __builtin_amdgcn_exp2f(-1.4426950408889634f * x)); }
; __device__ __forceinline__ u32x4 pack8(const f32x4 a, const f32x4 b) { u32x4 w; w.x = cvt_pk_bf16(a[0], a[1]); w.y = cvt_pk_bf16(a[2], a[3]); w.z = cvt_pk_bf16(b[0], b[1]); w.w = cvt_pk_bf16(b[2], b[3]); return w; }
; __device__ __forceinline__ void unpack8(const u32x4 w, f32x4& a, f32x4& b) { a = (f32x4){bf_lo(w.x), bf_hi(w.x), bf_lo(w.y), bf_hi(w.y)}; b = (f32x4){bf_lo(w.z), bf_hi(w.z), bf_lo(w.w), bf_hi(w.w)}; }
;     __device__ __forceinline__ void piece(size_t row, int col, f32x4 v0, f32x4 v1, const f32x4 b0, const f32x4 b1) const {
;     ...
;         if constexpr (MODE == 4) { f32x4 r0, r1; unpack8(*(const u32x4*)(res + row * ldr + col), r0, r1); v0 = v0 + b0; v1 = v1 + b1;
; #pragma unroll
;             for (int e = 0; e < 4; ++e) { v0[e] = r0[e] * sigmoidf_(v0[e]); v1[e] = r1[e] * sigmoidf_(v1[e]); }
;             *(u32x4*)((bf16_t*)O + row * ldo + col) = pack8(v0, v1); }
	v_lshlrev_b32_e32 v86, 16, v220
	v_and_b32_e32 v80, 0xffff0000, v220
	v_lshlrev_b32_e32 v88, 16, v222
	v_pk_add_f32 v[54:55], v[54:55], v[62:63]
	v_mul_f32_e32 v52, v52, v86
	v_mul_f32_e32 v86, v48, v88
	v_mul_f32_e32 v48, v53, v80
	v_add_f32_e32 v49, 1.0, v49
	v_mul_f32_e32 v53, 0xbfb8aa3b, v54
	v_rcp_f32_e32 v49, v49
	v_exp_f32_e32 v53, v53
	v_and_b32_e32 v82, 0xffff0000, v222
	v_pk_add_f32 v[50:51], v[50:51], v[58:59]
	v_mul_f32_e32 v54, v49, v82
	v_mul_f32_e32 v50, 0xbfb8aa3b, v50
	v_add_f32_e32 v49, 1.0, v53
	v_mul_f32_e32 v53, 0xbfb8aa3b, v55
	v_mul_f32_e32 v51, 0xbfb8aa3b, v51
	v_exp_f32_e32 v50, v50
	v_exp_f32_e32 v53, v53
	v_exp_f32_e32 v51, v51
	v_rcp_f32_e32 v49, v49
	v_add_f32_e32 v50, 1.0, v50
	v_add_f32_e32 v53, 1.0, v53
	v_add_f32_e32 v51, 1.0, v51
	v_rcp_f32_e32 v50, v50
	v_rcp_f32_e32 v53, v53
	v_rcp_f32_e32 v51, v51
	v_lshlrev_b32_e32 v87, 16, v221
	v_and_b32_e32 v81, 0xffff0000, v221
	v_lshlrev_b32_e32 v89, 16, v223
	v_and_b32_e32 v83, 0xffff0000, v223
	v_mul_f32_e32 v49, v49, v87
	v_mul_f32_e32 v55, v50, v89
	v_mul_f32_e32 v50, v53, v81
	v_mul_f32_e32 v51, v51, v83
	v_cvt_pk_bf16_f32 v48, v52, v48
	v_cvt_pk_bf16_f32 v49, v49, v50
	v_cvt_pk_bf16_f32 v50, v86, v54
	v_cvt_pk_bf16_f32 v51, v55, v51
	global_store_dwordx4 v[68:69], v[48:51], off offset:256
	v_pk_add_f32 v[44:45], v[44:45], v[76:77]
	v_pk_add_f32 v[40:41], v[40:41], v[72:73]
	v_mul_f32_e32 v44, 0xbfb8aa3b, v44
	v_mul_f32_e32 v40, 0xbfb8aa3b, v40
	v_mul_f32_e32 v45, 0xbfb8aa3b, v45
	v_exp_f32_e32 v44, v44
	v_exp_f32_e32 v40, v40
	v_exp_f32_e32 v45, v45
	v_mul_f32_e32 v41, 0xbfb8aa3b, v41
	v_add_f32_e32 v44, 1.0, v44
	v_add_f32_e32 v40, 1.0, v40
	v_add_f32_e32 v45, 1.0, v45
	v_rcp_f32_e32 v44, v44
	v_rcp_f32_e32 v40, v40
	v_rcp_f32_e32 v45, v45
	v_exp_f32_e32 v41, v41
	v_pk_add_f32 v[46:47], v[46:47], v[78:79]
	v_pk_add_f32 v[42:43], v[42:43], v[74:75]
	v_pk_add_f32 v[36:37], v[36:37], v[60:61]
	v_add_f32_e32 v41, 1.0, v41
	v_rcp_f32_e32 v41, v41
	v_mul_f32_e32 v42, 0xbfb8aa3b, v42
	v_exp_f32_e32 v42, v42
	v_mul_f32_e32 v43, 0xbfb8aa3b, v43
	s_waitcnt vmcnt(15)
	v_lshlrev_b32_e32 v52, 16, v224
	v_and_b32_e32 v53, 0xffff0000, v224
	v_lshlrev_b32_e32 v64, 16, v226
	v_mul_f32_e32 v44, v44, v52
	v_mul_f32_e32 v52, v40, v64
	v_mul_f32_e32 v40, v45, v53
	v_mul_f32_e32 v45, 0xbfb8aa3b, v46
	v_exp_f32_e32 v45, v45
	v_lshlrev_b32_e32 v54, 16, v225
	v_and_b32_e32 v55, 0xffff0000, v225
	v_and_b32_e32 v65, 0xffff0000, v226
	v_mul_f32_e32 v46, v41, v65
	v_add_f32_e32 v41, 1.0, v45
	v_mul_f32_e32 v45, 0xbfb8aa3b, v47
	v_exp_f32_e32 v45, v45
	v_exp_f32_e32 v43, v43
	v_add_f32_e32 v42, 1.0, v42
	v_rcp_f32_e32 v42, v42
	v_add_f32_e32 v45, 1.0, v45
	v_rcp_f32_e32 v45, v45
	v_add_f32_e32 v43, 1.0, v43
	v_rcp_f32_e32 v41, v41
	v_rcp_f32_e32 v43, v43
	v_lshlrev_b32_e32 v66, 16, v227
	v_mul_f32_e32 v47, v42, v66
	v_mul_f32_e32 v42, v45, v55
	v_cvt_pk_bf16_f32 v40, v44, v40
	v_lshlrev_b64 v[44:45], 11, v[70:71]
	v_and_b32_e32 v67, 0xffff0000, v227
	v_lshl_add_u64 v[44:45], s[8:9], 0, v[44:45]
	v_mul_f32_e32 v41, v41, v54
	v_mul_f32_e32 v43, v43, v67
	v_lshl_add_u64 v[44:45], v[44:45], 0, v[160:161]
	v_cvt_pk_bf16_f32 v41, v41, v42
	v_cvt_pk_bf16_f32 v42, v52, v46
	v_cvt_pk_bf16_f32 v43, v47, v43
	global_store_dwordx4 v[44:45], v[40:43], off
	v_pk_add_f32 v[32:33], v[32:33], v[56:57]
	v_mul_f32_e32 v36, 0xbfb8aa3b, v36
	v_add_u32_e32 v40, 0xa0, v162
	v_ashrrev_i32_e32 v41, 31, v40
	v_lshl_add_u64 v[46:47], v[40:41], 0, s[18:19]
	v_lshlrev_b64 v[40:41], 10, v[46:47]
	v_lshl_add_u64 v[40:41], s[46:47], 0, v[40:41]
	v_lshl_add_u64 v[52:53], v[40:41], 0, v[160:161]
	v_mul_f32_e32 v32, 0xbfb8aa3b, v32
	v_mul_f32_e32 v37, 0xbfb8aa3b, v37
	v_exp_f32_e32 v36, v36
	v_exp_f32_e32 v32, v32
	v_exp_f32_e32 v37, v37
	v_mul_f32_e32 v33, 0xbfb8aa3b, v33
	v_add_f32_e32 v36, 1.0, v36
	v_add_f32_e32 v32, 1.0, v32
	v_add_f32_e32 v37, 1.0, v37
	v_rcp_f32_e32 v36, v36
	v_rcp_f32_e32 v32, v32
	v_rcp_f32_e32 v37, v37
	v_exp_f32_e32 v33, v33
	s_waitcnt vmcnt(15)
	v_lshlrev_b32_e32 v54, 16, v228
	v_and_b32_e32 v48, 0xffff0000, v228
	v_lshlrev_b32_e32 v64, 16, v230
	v_pk_add_f32 v[38:39], v[38:39], v[62:63]
	v_mul_f32_e32 v36, v36, v54
	v_mul_f32_e32 v54, v32, v64
	v_mul_f32_e32 v32, v37, v48
	v_add_f32_e32 v33, 1.0, v33
	v_mul_f32_e32 v37, 0xbfb8aa3b, v38
	v_rcp_f32_e32 v33, v33
	v_exp_f32_e32 v37, v37
	v_and_b32_e32 v50, 0xffff0000, v230
	v_pk_add_f32 v[34:35], v[34:35], v[58:59]
	v_mul_f32_e32 v38, v33, v50
	v_mul_f32_e32 v34, 0xbfb8aa3b, v34
	v_add_f32_e32 v33, 1.0, v37
	v_mul_f32_e32 v37, 0xbfb8aa3b, v39
	v_mul_f32_e32 v35, 0xbfb8aa3b, v35
	v_exp_f32_e32 v34, v34
	v_exp_f32_e32 v37, v37
	v_exp_f32_e32 v35, v35
	v_rcp_f32_e32 v33, v33
	v_add_f32_e32 v34, 1.0, v34
	v_add_f32_e32 v37, 1.0, v37
	v_add_f32_e32 v35, 1.0, v35
	v_rcp_f32_e32 v34, v34
	v_rcp_f32_e32 v37, v37
	v_rcp_f32_e32 v35, v35
	v_lshlrev_b32_e32 v55, 16, v229
	v_and_b32_e32 v49, 0xffff0000, v229
	v_lshlrev_b32_e32 v65, 16, v231
	v_and_b32_e32 v51, 0xffff0000, v231
	v_mul_f32_e32 v33, v33, v55
	v_mul_f32_e32 v39, v34, v65
	v_mul_f32_e32 v34, v37, v49
	v_mul_f32_e32 v35, v35, v51
	v_cvt_pk_bf16_f32 v32, v36, v32
	v_cvt_pk_bf16_f32 v33, v33, v34
	v_cvt_pk_bf16_f32 v34, v54, v38
	v_cvt_pk_bf16_f32 v35, v39, v35
	global_store_dwordx4 v[44:45], v[32:35], off offset:256
	v_pk_add_f32 v[28:29], v[28:29], v[76:77]
	v_pk_add_f32 v[24:25], v[24:25], v[72:73]
	v_mul_f32_e32 v28, 0xbfb8aa3b, v28
	v_mul_f32_e32 v24, 0xbfb8aa3b, v24
	v_mul_f32_e32 v29, 0xbfb8aa3b, v29
	v_exp_f32_e32 v28, v28
	v_exp_f32_e32 v24, v24
	v_exp_f32_e32 v29, v29
	v_mul_f32_e32 v25, 0xbfb8aa3b, v25
	v_add_f32_e32 v28, 1.0, v28
	v_add_f32_e32 v24, 1.0, v24
	v_add_f32_e32 v29, 1.0, v29
	v_rcp_f32_e32 v28, v28
	v_rcp_f32_e32 v24, v24
	v_rcp_f32_e32 v29, v29
	v_exp_f32_e32 v25, v25
	v_pk_add_f32 v[30:31], v[30:31], v[78:79]
	v_pk_add_f32 v[26:27], v[26:27], v[74:75]
	v_pk_add_f32 v[20:21], v[20:21], v[60:61]
	v_add_f32_e32 v25, 1.0, v25
	v_rcp_f32_e32 v25, v25
	v_mul_f32_e32 v26, 0xbfb8aa3b, v26
	v_exp_f32_e32 v26, v26
	v_mul_f32_e32 v27, 0xbfb8aa3b, v27
	v_exp_f32_e32 v27, v27
	v_pk_add_f32 v[16:17], v[16:17], v[56:57]
	s_waitcnt vmcnt(15)
; __device__ __forceinline__ float sigmoidf_(float x) { return __builtin_amdgcn_rcpf(1.f + __builtin_amdgcn_exp2f(-1.4426950408889634f * x)); }
; #define PG8_BAR __builtin_amdgcn_s_barrier()
; __device__ __forceinline__ u32x4 pack8(const f32x4 a, const f32x4 b) { u32x4 w; w.x = cvt_pk_bf16(a[0], a[1]); w.y = cvt_pk_bf16(a[2], a[3]); w.z = cvt_pk_bf16(b[0], b[1]); w.w = cvt_pk_bf16(b[2], b[3]); return w; }
; __device__ __forceinline__ void unpack8(const u32x4 w, f32x4& a, f32x4& b) { a = (f32x4){bf_lo(w.x), bf_hi(w.x), bf_lo(w.y), bf_hi(w.y)}; b = (f32x4){bf_lo(w.z), bf_hi(w.z), bf_lo(w.w), bf_hi(w.w)}; }
; template <class Epi, class Sched, bool ALIGN_EPI>
; __device__ __forceinline__ void gemm_phase(LAS unsigned char* lds, const GemmDesc g, const Sched& S, const Epi& E) {
;     ...
;         if (!has_next) break;
; #pragma unroll
;         for (int a = 0; a < 2; ++a)
; #pragma unroll
;             for (int b = 0; b < 2; ++b)
; #pragma unroll
;                 for (int m = 0; m < 4; ++m)
; #pragma unroll
;                     for (int n = 0; n < 2; ++n) acc[a][b][m][n] = (f32x4){0.f, 0.f, 0.f, 0.f};
;         cur = nxt; cA = nA; cB = nB; ++ui;
;         if constexpr (ALIGN_EPI) { if (wr == 1) PG8_BAR; }
;     }
;     __device__ __forceinline__ void piece(size_t row, int col, f32x4 v0, f32x4 v1, const f32x4 b0, const f32x4 b1) const {
;     ...
;         if constexpr (MODE == 4) { f32x4 r0, r1; unpack8(*(const u32x4*)(res + row * ldr + col), r0, r1); v0 = v0 + b0; v1 = v1 + b1;
; #pragma unroll
;             for (int e = 0; e < 4; ++e) { v0[e] = r0[e] * sigmoidf_(v0[e]); v1[e] = r1[e] * sigmoidf_(v1[e]); }
;             *(u32x4*)((bf16_t*)O + row * ldo + col) = pack8(v0, v1); }
	v_lshlrev_b32_e32 v36, 16, v232
	v_and_b32_e32 v37, 0xffff0000, v232
	v_lshlrev_b32_e32 v40, 16, v234
	v_mul_f32_e32 v28, v28, v36
	v_mul_f32_e32 v36, v24, v40
	v_mul_f32_e32 v24, v29, v37
	v_mul_f32_e32 v29, 0xbfb8aa3b, v30
	v_exp_f32_e32 v29, v29
	v_lshlrev_b32_e32 v38, 16, v233
	v_and_b32_e32 v39, 0xffff0000, v233
	v_and_b32_e32 v41, 0xffff0000, v234
	v_mul_f32_e32 v30, v25, v41
	v_add_f32_e32 v25, 1.0, v29
	v_mul_f32_e32 v29, 0xbfb8aa3b, v31
	v_exp_f32_e32 v29, v29
	v_add_f32_e32 v26, 1.0, v26
	v_rcp_f32_e32 v26, v26
	v_add_f32_e32 v27, 1.0, v27
	v_add_f32_e32 v29, 1.0, v29
	v_rcp_f32_e32 v29, v29
	v_rcp_f32_e32 v25, v25
	v_rcp_f32_e32 v27, v27
	v_lshlrev_b32_e32 v42, 16, v235
	v_mul_f32_e32 v31, v26, v42
	v_mul_f32_e32 v26, v29, v39
	v_cvt_pk_bf16_f32 v24, v28, v24
	v_lshlrev_b64 v[28:29], 11, v[46:47]
	v_and_b32_e32 v43, 0xffff0000, v235
	v_lshl_add_u64 v[28:29], s[8:9], 0, v[28:29]
	v_mul_f32_e32 v20, 0xbfb8aa3b, v20
	v_mul_f32_e32 v16, 0xbfb8aa3b, v16
	v_mul_f32_e32 v21, 0xbfb8aa3b, v21
	v_mul_f32_e32 v25, v25, v38
	v_mul_f32_e32 v27, v27, v43
	v_lshl_add_u64 v[28:29], v[28:29], 0, v[160:161]
	v_exp_f32_e32 v20, v20
	v_exp_f32_e32 v16, v16
	v_exp_f32_e32 v21, v21
	v_cvt_pk_bf16_f32 v25, v25, v26
	v_cvt_pk_bf16_f32 v26, v36, v30
	v_cvt_pk_bf16_f32 v27, v31, v27
	global_store_dwordx4 v[28:29], v[24:27], off
	v_add_f32_e32 v20, 1.0, v20
	v_add_f32_e32 v16, 1.0, v16
	v_add_u32_e32 v24, 0xb0, v162
	v_ashrrev_i32_e32 v25, 31, v24
	v_lshl_add_u64 v[30:31], v[24:25], 0, s[18:19]
	v_lshlrev_b64 v[24:25], 10, v[30:31]
	v_add_f32_e32 v21, 1.0, v21
	v_mul_f32_e32 v17, 0xbfb8aa3b, v17
	v_lshl_add_u64 v[24:25], s[46:47], 0, v[24:25]
	v_rcp_f32_e32 v20, v20
	v_rcp_f32_e32 v16, v16
	v_rcp_f32_e32 v21, v21
	v_exp_f32_e32 v17, v17
	v_lshl_add_u64 v[36:37], v[24:25], 0, v[160:161]
	s_waitcnt vmcnt(15)
	v_lshlrev_b32_e32 v38, 16, v236
	v_and_b32_e32 v32, 0xffff0000, v236
	v_lshlrev_b32_e32 v40, 16, v238
	v_pk_add_f32 v[22:23], v[22:23], v[62:63]
	v_mul_f32_e32 v20, v20, v38
	v_mul_f32_e32 v38, v16, v40
	v_mul_f32_e32 v16, v21, v32
	v_add_f32_e32 v17, 1.0, v17
	v_mul_f32_e32 v21, 0xbfb8aa3b, v22
	v_rcp_f32_e32 v17, v17
	v_exp_f32_e32 v21, v21
	v_and_b32_e32 v34, 0xffff0000, v238
	v_pk_add_f32 v[18:19], v[18:19], v[58:59]
	v_mul_f32_e32 v22, v17, v34
	v_mul_f32_e32 v18, 0xbfb8aa3b, v18
	v_add_f32_e32 v17, 1.0, v21
	v_mul_f32_e32 v21, 0xbfb8aa3b, v23
	v_mul_f32_e32 v19, 0xbfb8aa3b, v19
	v_exp_f32_e32 v18, v18
	v_exp_f32_e32 v21, v21
	v_exp_f32_e32 v19, v19
	v_rcp_f32_e32 v17, v17
	v_add_f32_e32 v18, 1.0, v18
	v_add_f32_e32 v21, 1.0, v21
	v_add_f32_e32 v19, 1.0, v19
	v_rcp_f32_e32 v18, v18
	v_rcp_f32_e32 v21, v21
	v_rcp_f32_e32 v19, v19
	v_lshlrev_b32_e32 v39, 16, v237
	v_and_b32_e32 v33, 0xffff0000, v237
	v_lshlrev_b32_e32 v41, 16, v239
	v_and_b32_e32 v35, 0xffff0000, v239
	v_mul_f32_e32 v17, v17, v39
	v_mul_f32_e32 v23, v18, v41
	v_mul_f32_e32 v18, v21, v33
	v_mul_f32_e32 v19, v19, v35
	v_cvt_pk_bf16_f32 v16, v20, v16
	v_cvt_pk_bf16_f32 v17, v17, v18
	v_cvt_pk_bf16_f32 v18, v38, v22
	v_cvt_pk_bf16_f32 v19, v23, v19
	global_store_dwordx4 v[28:29], v[16:19], off offset:256
	v_pk_add_f32 v[12:13], v[12:13], v[76:77]
	v_pk_add_f32 v[8:9], v[8:9], v[72:73]
	v_mul_f32_e32 v12, 0xbfb8aa3b, v12
	v_mul_f32_e32 v8, 0xbfb8aa3b, v8
	v_mul_f32_e32 v13, 0xbfb8aa3b, v13
	v_exp_f32_e32 v12, v12
	v_exp_f32_e32 v8, v8
	v_exp_f32_e32 v13, v13
	v_mul_f32_e32 v9, 0xbfb8aa3b, v9
	v_add_f32_e32 v12, 1.0, v12
	v_add_f32_e32 v8, 1.0, v8
	v_add_f32_e32 v13, 1.0, v13
	v_rcp_f32_e32 v12, v12
	v_rcp_f32_e32 v8, v8
	v_rcp_f32_e32 v13, v13
	v_exp_f32_e32 v9, v9
	v_pk_add_f32 v[14:15], v[14:15], v[78:79]
	v_pk_add_f32 v[10:11], v[10:11], v[74:75]
	v_pk_add_f32 v[4:5], v[4:5], v[60:61]
	v_add_f32_e32 v9, 1.0, v9
	v_rcp_f32_e32 v9, v9
	v_mul_f32_e32 v10, 0xbfb8aa3b, v10
	v_exp_f32_e32 v10, v10
	v_mul_f32_e32 v11, 0xbfb8aa3b, v11
	v_exp_f32_e32 v11, v11
	v_pk_add_f32 v[0:1], v[0:1], v[56:57]
	v_mul_f32_e32 v4, 0xbfb8aa3b, v4
	v_mul_f32_e32 v0, 0xbfb8aa3b, v0
	v_mul_f32_e32 v5, 0xbfb8aa3b, v5
	v_add_f32_e32 v10, 1.0, v10
	v_exp_f32_e32 v4, v4
	v_exp_f32_e32 v0, v0
	v_exp_f32_e32 v5, v5
	v_rcp_f32_e32 v10, v10
	v_add_f32_e32 v11, 1.0, v11
	v_rcp_f32_e32 v11, v11
	v_add_f32_e32 v4, 1.0, v4
	s_waitcnt vmcnt(15)
	v_lshlrev_b32_e32 v20, 16, v240
	v_and_b32_e32 v21, 0xffff0000, v240
	v_lshlrev_b32_e32 v24, 16, v242
	v_mul_f32_e32 v12, v12, v20
	v_mul_f32_e32 v20, v8, v24
	v_mul_f32_e32 v8, v13, v21
	v_mul_f32_e32 v13, 0xbfb8aa3b, v14
	v_exp_f32_e32 v13, v13
	v_lshlrev_b32_e32 v22, 16, v241
	v_and_b32_e32 v23, 0xffff0000, v241
	v_and_b32_e32 v25, 0xffff0000, v242
	v_mul_f32_e32 v14, v9, v25
	v_add_f32_e32 v9, 1.0, v13
	v_mul_f32_e32 v13, 0xbfb8aa3b, v15
	v_exp_f32_e32 v13, v13
	v_rcp_f32_e32 v9, v9
	v_lshlrev_b32_e32 v26, 16, v243
	v_add_f32_e32 v0, 1.0, v0
	v_add_f32_e32 v13, 1.0, v13
	v_rcp_f32_e32 v13, v13
	v_add_f32_e32 v5, 1.0, v5
	v_mul_f32_e32 v1, 0xbfb8aa3b, v1
	v_mul_f32_e32 v15, v10, v26
	v_mul_f32_e32 v10, v13, v23
	v_cvt_pk_bf16_f32 v8, v12, v8
	v_lshlrev_b64 v[12:13], 11, v[30:31]
	v_rcp_f32_e32 v4, v4
	v_rcp_f32_e32 v0, v0
	v_rcp_f32_e32 v5, v5
	v_exp_f32_e32 v1, v1
	v_and_b32_e32 v27, 0xffff0000, v243
	v_mul_f32_e32 v9, v9, v22
	v_lshl_add_u64 v[12:13], s[8:9], 0, v[12:13]
	v_mul_f32_e32 v11, v11, v27
	v_cvt_pk_bf16_f32 v9, v9, v10
	v_lshl_add_u64 v[12:13], v[12:13], 0, v[160:161]
	v_cvt_pk_bf16_f32 v10, v20, v14
	v_cvt_pk_bf16_f32 v11, v15, v11
	global_store_dwordx4 v[12:13], v[8:11], off
	v_pk_add_f32 v[6:7], v[6:7], v[62:63]
	v_add_f32_e32 v1, 1.0, v1
	v_rcp_f32_e32 v1, v1
	s_waitcnt vmcnt(15)
	v_lshlrev_b32_e32 v8, 16, v244
	v_and_b32_e32 v9, 0xffff0000, v244
	v_lshlrev_b32_e32 v14, 16, v246
	v_mul_f32_e32 v4, v4, v8
	v_mul_f32_e32 v8, v0, v14
	v_mul_f32_e32 v0, v5, v9
	v_mul_f32_e32 v5, 0xbfb8aa3b, v6
	v_exp_f32_e32 v5, v5
	v_and_b32_e32 v15, 0xffff0000, v246
	v_pk_add_f32 v[2:3], v[2:3], v[58:59]
	v_mul_f32_e32 v6, v1, v15
	v_mul_f32_e32 v2, 0xbfb8aa3b, v2
	v_add_f32_e32 v1, 1.0, v5
	v_mul_f32_e32 v5, 0xbfb8aa3b, v7
	v_mul_f32_e32 v3, 0xbfb8aa3b, v3
	v_exp_f32_e32 v2, v2
	v_exp_f32_e32 v5, v5
	v_exp_f32_e32 v3, v3
	v_rcp_f32_e32 v1, v1
	v_add_f32_e32 v2, 1.0, v2
	v_add_f32_e32 v5, 1.0, v5
	v_add_f32_e32 v3, 1.0, v3
	v_rcp_f32_e32 v2, v2
	v_rcp_f32_e32 v5, v5
	v_rcp_f32_e32 v3, v3
	v_lshlrev_b32_e32 v10, 16, v245
	v_and_b32_e32 v11, 0xffff0000, v245
	v_lshlrev_b32_e32 v16, 16, v247
	v_and_b32_e32 v17, 0xffff0000, v247
	v_mul_f32_e32 v1, v1, v10
	v_mul_f32_e32 v7, v2, v16
	v_mul_f32_e32 v2, v5, v11
	v_mul_f32_e32 v3, v3, v17
	v_cvt_pk_bf16_f32 v0, v4, v0
	v_cvt_pk_bf16_f32 v1, v1, v2
	v_cvt_pk_bf16_f32 v2, v8, v6
	v_cvt_pk_bf16_f32 v3, v7, v3
	global_store_dwordx4 v[12:13], v[0:3], off offset:256
	s_cbranch_vccnz .LBB0_732
	s_andn2_b64 vcc, exec, s[0:1]
	s_cbranch_vccnz .LBB0_731
	s_barrier
	s_branch .LBB0_731
